# in-proj layer-1 XCD permutation variant: homogeneous rounds (all XCDs K0,K0 then T; XCD 7 K0ctx,T,T)
# baseline (speedup 1.0000x reference)
;     __device__ __forceinline__ bool idx(int i, int& Lp, int& half) const {
;         const int R = n / G, T = n % G; long L; half = 0;
;         if (i == R && T > 0 && 2 * T <= G) { if (c >= 2 * T) return false; L = (long)R * G + (c >> 1); half = 1 + (c & 1); }
;         else { L = (long)i * G + c; if (L >= n) return false; }
;         const int w = (int)L, q = n / 8, r = n % 8, xcd = w % 8, off = w / 8;
;         Lp = (xcd < r ? xcd * (q + 1) : r * (q + 1) + (xcd - r) * q) + off; return true;
;     __device__ __forceinline__ bool next(int i, Unit& u) const {
;     ...
;         if (!l1) { if (q < 504) { kind = 0; const int gid = q / 56, rem = q % 56; pm = gid * 8 + (rem & 7); pn = rem >> 3; } else if (q < 760) { const int s = q - 504; kind = 1; bt = s >> 5; pn = (s & 31) >> 2; pm = s & 3; } else { const int s = q - 760; kind = 2; bt = s >> 2; pm = s & 3; pn = 0; } }
;         else { if (q < 448) { kind = 0; const int gid = q / 56, rem = q % 56; pm = gid * 8 + (rem & 7); pn = rem >> 3; } else if (q < 488) { const int s = q - 448, r5 = s % 5; kind = 0; pm = 64 + s / 5; pn = r5 < 4 ? r5 + 1 : 6; }
;                else if (q < 744) { const int s = q - 488; kind = 1; bt = s >> 5; pn = (s & 31) >> 2; pm = s & 3; } else { const int s = q - 744; kind = 2; bt = s / 3; pm = 1 + s % 3; pn = 0; } }
.LBB0_375:
	v_readlane_b32 s10, v255, 20
	v_readlane_b32 s11, v255, 21
	s_mov_b64 s[4:5], -1
	s_and_b64 vcc, exec, s[10:11]
	s_cbranch_vccz .LBB0_387
	s_lshr_b32 s18, s19, 5
	s_mul_i32 s20, s18, 11
	s_lshr_b32 s20, s20, 5
	s_mul_i32 s22, s20, 3
	s_sub_i32 s22, s18, s22
	s_lshl_b32 s23, s20, 1
	s_add_i32 s23, s23, s22
	s_cmp_lt_u32 s20, 7
	s_cbranch_scc0 .Lperm_hi_a
	s_add_i32 s18, s20, 15
	s_cmp_lt_u32 s22, 2
	s_cselect_b32 s23, s23, s18
	s_branch .Lperm_done_a

;     __device__ __forceinline__ bool idx(int i, int& Lp, int& half) const {
;         const int R = n / G, T = n % G; long L; half = 0;
;         if (i == R && T > 0 && 2 * T <= G) { if (c >= 2 * T) return false; L = (long)R * G + (c >> 1); half = 1 + (c & 1); }
;         else { L = (long)i * G + c; if (L >= n) return false; }
;         const int w = (int)L, q = n / 8, r = n % 8, xcd = w % 8, off = w / 8;
;         Lp = (xcd < r ? xcd * (q + 1) : r * (q + 1) + (xcd - r) * q) + off; return true;
;     __device__ __forceinline__ bool next(int i, Unit& u) const {
;     ...
;         if (!l1) { if (q < 504) { kind = 0; const int gid = q / 56, rem = q % 56; pm = gid * 8 + (rem & 7); pn = rem >> 3; } else if (q < 760) { const int s = q - 504; kind = 1; bt = s >> 5; pn = (s & 31) >> 2; pm = s & 3; } else { const int s = q - 760; kind = 2; bt = s >> 2; pm = s & 3; pn = 0; } }
;         else { if (q < 448) { kind = 0; const int gid = q / 56, rem = q % 56; pm = gid * 8 + (rem & 7); pn = rem >> 3; } else if (q < 488) { const int s = q - 448, r5 = s % 5; kind = 0; pm = 64 + s / 5; pn = r5 < 4 ? r5 + 1 : 6; }
;                else if (q < 744) { const int s = q - 488; kind = 1; bt = s >> 5; pn = (s & 31) >> 2; pm = s & 3; } else { const int s = q - 744; kind = 2; bt = s / 3; pm = 1 + s % 3; pn = 0; } }
.LBB0_415:
	s_xor_b64 s[26:27], s[30:31], -1
	s_and_b64 vcc, exec, s[26:27]
	s_mov_b64 s[36:37], s[14:15]
	s_mov_b64 s[34:35], s[10:11]
	s_cbranch_vccnz .LBB0_446
	v_readlane_b32 s12, v255, 20
	v_readlane_b32 s13, v255, 21
	s_mov_b64 s[4:5], -1
	s_and_b64 vcc, exec, s[12:13]
	s_cbranch_vccz .LBB0_428
	s_lshr_b32 s8, s9, 5
	s_mul_i32 s28, s8, 11
	s_lshr_b32 s28, s28, 5
	s_mul_i32 s38, s28, 3
	s_sub_i32 s38, s8, s38
	s_lshl_b32 s39, s28, 1
	s_add_i32 s39, s39, s38
	s_cmp_lt_u32 s28, 7
	s_cbranch_scc0 .Lperm_hi_b
	s_add_i32 s8, s28, 15
	s_cmp_lt_u32 s38, 2
	s_cselect_b32 s39, s39, s8
	s_branch .Lperm_done_b
